# v86 + RG-LRU pass-2 output tail (hs * gelu_tanh(g), 16 channels per lane) evaluated with packed f32 ops on bf16 word pairs, LDS reads issued up front; same per-element operation sequence
# speedup vs baseline: 1.0043x; 1.0043x over previous
; #define LAS __attribute__((address_space(3)))
; __device__ __forceinline__ float bf2f(unsigned short v) { return __uint_as_float(((unsigned)v) << 16); }
; template <int PASS>
; __device__ __forceinline__ void rglru_phase(const Ctx& F, int l, const bf16_t* XRb, bf16_t* GRb, bool latent_only = false) {
;     ...
;             if (PASS == 2) { const bf16_t* gp = GRb + (size_t)(seg_row0 + tl0 + lane) * 1024 + blk * 128 + cw; g0 = *(const u32x4*)gp; g1 = *(const u32x4*)(gp + 8); }
;             float aggA[2] = {1.f, 1.f}, aggB[2] = {0.f, 0.f};
;             float hF = PASS == 2 ? CAR[(0 * 9 + (c - c0)) * 16 + l15] : 0.f;
;             float hfv[4][4], ba_[4][4], bb_[4][4], bAe[4], bBe[4], bAt[4], bBt[4];
; #pragma unroll
;             for (int mt = 0; mt < 4; ++mt) {
;                 f32x4 ag[4];
; #pragma unroll
;                 for (int gt = 0; gt < 4; ++gt) { const float nb = (gt & 1) ? nbx[gt >> 1] : nba[gt >> 1]; ag[gt] = (f32x4){nb, nb, nb, nb}; }
; #pragma unroll
;                 for (int ks = 0; ks < 4; ++ks) { const bf16x8 af = *(const LAS bf16x8*)(XT + (mt * 16 + l15) * XT_LD + ks * 32 + 8 * l4);
; #pragma unroll
;                     for (int gt = 0; gt < 4; ++gt) ag[gt] = __builtin_amdgcn_mfma_f32_16x16x32_bf16(af, Bf[gt][ks], ag[gt], 0, 0, 0); }
;                 float ea[2][4], eb[2][4];
; #pragma unroll
;                 for (int r = 0; r < 4; ++r) { const int tok = mt * 16 + 4 * l4 + r;
;                     const float xv = bf2f(XT[tok * XT_LD + cw + l15]);
; #pragma unroll
;                     for (int d = 0; d < 2; ++d) {
;                         const float e1 = 1.0f + __builtin_amdgcn_exp2f(ag[2 * d][r]), e2 = 1.0f + __builtin_amdgcn_exp2f(ag[2 * d + 1][r]);
;                         const float inv = __builtin_amdgcn_rcpf(e1 * e2); const float rgate = e2 * inv, igate = e1 * inv;
;                         const float a = __builtin_amdgcn_exp2f(rgate * cl2[d]);
;                         const float om = fmaf(-a, a, 1.0f);
;                         const float bv = __builtin_amdgcn_sqrtf(om) * (igate * xv);
;                         ea[d][r] = a; eb[d][r] = bv; } }
.LBB0_509:
	s_add_i32 s18, s39, 0xffffff00
	s_cmp_lt_u32 s38, 4
	s_cselect_b32 s19, s22, s23
	s_cselect_b32 s18, s39, s18
	s_add_i32 s18, s18, s19
	v_add_u32_e32 v34, s18, v166
	v_ashrrev_i32_e32 v35, 31, v34
	v_lshlrev_b64 v[34:35], 11, v[34:35]
	v_lshl_add_u64 v[34:35], s[20:21], 0, v[34:35]
	global_load_dwordx4 v[116:119], v[34:35], off offset:16
	global_load_dwordx4 v[120:123], v[34:35], off
	ds_read_b32 v201, v187
	ds_read_b128 v[124:127], v180
	ds_read_b128 v[160:163], v180 offset:64
	ds_read_u16 v32, v181
	s_waitcnt lgkmcnt(2)
	v_mfma_f32_16x16x32_bf16 v[128:131], v[124:127], v[0:3], v[100:103]
	s_and_b64 vcc, exec, s[62:63]
	s_mov_b32 s39, s33
	s_mov_b32 s38, s8
	v_mfma_f32_16x16x32_bf16 v[132:135], v[124:127], v[16:19], v[104:107]
	v_mfma_f32_16x16x32_bf16 v[136:139], v[124:127], v[36:39], v[108:111]
	v_mfma_f32_16x16x32_bf16 v[124:127], v[124:127], v[52:55], v[112:115]
	s_waitcnt lgkmcnt(1)
	v_mfma_f32_16x16x32_bf16 v[128:131], v[160:163], v[4:7], v[128:131]
	v_mfma_f32_16x16x32_bf16 v[132:135], v[160:163], v[20:23], v[132:135]
	v_mfma_f32_16x16x32_bf16 v[136:139], v[160:163], v[40:43], v[136:139]
	v_mfma_f32_16x16x32_bf16 v[124:127], v[160:163], v[56:59], v[124:127]
	ds_read_b128 v[160:163], v180 offset:128
	s_waitcnt lgkmcnt(0)
	v_mfma_f32_16x16x32_bf16 v[128:131], v[160:163], v[8:11], v[128:131]
	v_mfma_f32_16x16x32_bf16 v[132:135], v[160:163], v[24:27], v[132:135]
	v_mfma_f32_16x16x32_bf16 v[188:191], v[160:163], v[44:47], v[136:139]
	v_mfma_f32_16x16x32_bf16 v[124:127], v[160:163], v[60:63], v[124:127]
	ds_read_b128 v[160:163], v180 offset:192
	s_waitcnt lgkmcnt(0)
	v_mfma_f32_16x16x32_bf16 v[136:139], v[160:163], v[12:15], v[128:131]
	v_mfma_f32_16x16x32_bf16 v[132:135], v[160:163], v[28:31], v[132:135]
	v_mfma_f32_16x16x32_bf16 v[128:131], v[160:163], v[48:51], v[188:191]
	v_mfma_f32_16x16x32_bf16 v[124:127], v[160:163], v[64:67], v[124:127]
	v_lshlrev_b32_e32 v160, 16, v32
	s_nop 3
	v_exp_f32_e32 v32, v136
	v_exp_f32_e32 v132, v132
	v_exp_f32_e32 v128, v128
	v_exp_f32_e32 v133, v133
	v_add_f32_e32 v32, 1.0, v32
	v_add_f32_e32 v132, 1.0, v132
	v_mul_f32_e32 v136, v32, v132
	v_rcp_f32_e32 v136, v136
	v_exp_f32_e32 v124, v124
	v_add_f32_e32 v128, 1.0, v128
	v_add_f32_e32 v133, 1.0, v133
	v_mul_f32_e32 v132, v132, v136
	v_mul_f32_e32 v132, v185, v132
	v_exp_f32_e32 v132, v132
	v_mul_f32_e32 v32, v32, v136
	v_mul_f32_e32 v32, v32, v160
	v_add_f32_e32 v124, 1.0, v124
	v_fma_f32 v136, -v132, v132, 1.0
	v_sqrt_f32_e32 v136, v136
	v_exp_f32_e32 v125, v125
	v_exp_f32_e32 v126, v126
	v_exp_f32_e32 v127, v127
	v_mul_f32_e32 v32, v32, v136
	v_mul_f32_e32 v136, v128, v124
	v_rcp_f32_e32 v136, v136
	v_add_f32_e32 v125, 1.0, v125
	v_add_f32_e32 v126, 1.0, v126
	v_add_f32_e32 v127, 1.0, v127
	v_mul_f32_e32 v124, v124, v136
	v_mul_f32_e32 v124, v186, v124
	v_exp_f32_e32 v188, v124
	v_mul_f32_e32 v128, v128, v136
	v_mul_f32_e32 v128, v128, v160
	ds_read_b128 v[160:163], v180 offset:4416
	v_fma_f32 v124, -v188, v188, 1.0
	v_sqrt_f32_e32 v124, v124
	s_nop 0
	v_mul_f32_e32 v189, v128, v124
	v_exp_f32_e32 v128, v137
	ds_read_u16 v124, v181 offset:272
	v_add_f32_e32 v128, 1.0, v128
	v_mul_f32_e32 v136, v128, v133
	v_rcp_f32_e32 v136, v136
	s_waitcnt lgkmcnt(0)
	v_lshlrev_b32_e32 v124, 16, v124
	v_mul_f32_e32 v133, v133, v136
	v_mul_f32_e32 v133, v185, v133
	v_exp_f32_e32 v133, v133
	v_mul_f32_e32 v128, v128, v136
	v_mul_f32_e32 v128, v128, v124
	v_fma_f32 v136, -v133, v133, 1.0
	v_sqrt_f32_e32 v136, v136
	s_nop 0
	v_mul_f32_e32 v190, v128, v136
	v_exp_f32_e32 v128, v129
	s_nop 0
	v_add_f32_e32 v128, 1.0, v128
	v_mul_f32_e32 v129, v128, v125
	v_rcp_f32_e32 v129, v129
	s_nop 0
	v_mul_f32_e32 v125, v125, v129
	v_mul_f32_e32 v125, v186, v125
	v_exp_f32_e32 v191, v125
	v_mul_f32_e32 v128, v128, v129
	v_mul_f32_e32 v124, v128, v124
	v_exp_f32_e32 v128, v134
	v_fma_f32 v125, -v191, v191, 1.0
	v_sqrt_f32_e32 v125, v125
	v_add_f32_e32 v128, 1.0, v128
	v_mul_f32_e32 v192, v124, v125
	v_exp_f32_e32 v125, v138
	ds_read_u16 v124, v181 offset:544
	v_add_f32_e32 v125, 1.0, v125
	v_mul_f32_e32 v129, v125, v128
	v_rcp_f32_e32 v129, v129
	s_waitcnt lgkmcnt(0)
	v_lshlrev_b32_e32 v124, 16, v124
	v_mul_f32_e32 v128, v128, v129
	v_mul_f32_e32 v128, v185, v128
	v_exp_f32_e32 v128, v128
	v_mul_f32_e32 v125, v125, v129
	v_mul_f32_e32 v125, v125, v124
	v_fma_f32 v129, -v128, v128, 1.0
	v_sqrt_f32_e32 v129, v129
	s_nop 0
	v_mul_f32_e32 v193, v125, v129
	v_exp_f32_e32 v125, v130
	s_nop 0
	v_add_f32_e32 v125, 1.0, v125
	v_mul_f32_e32 v129, v125, v126
	v_rcp_f32_e32 v129, v129
	s_nop 0
	v_mul_f32_e32 v126, v126, v129
	v_mul_f32_e32 v126, v186, v126
	v_exp_f32_e32 v194, v126
	v_mul_f32_e32 v125, v125, v129
	v_mul_f32_e32 v124, v125, v124
	v_exp_f32_e32 v125, v139
	v_fma_f32 v126, -v194, v194, 1.0
	v_sqrt_f32_e32 v126, v126
	v_add_f32_e32 v125, 1.0, v125
	v_mul_f32_e32 v195, v124, v126
	v_exp_f32_e32 v126, v135
	ds_read_u16 v124, v181 offset:816
	v_add_f32_e32 v126, 1.0, v126
	v_mul_f32_e32 v129, v125, v126
	v_rcp_f32_e32 v129, v129
	s_waitcnt lgkmcnt(0)
	v_lshlrev_b32_e32 v124, 16, v124
	v_mul_f32_e32 v126, v126, v129
	v_mul_f32_e32 v126, v185, v126
	v_exp_f32_e32 v126, v126
	v_mul_f32_e32 v125, v125, v129
	v_mul_f32_e32 v125, v125, v124
	v_fma_f32 v129, -v126, v126, 1.0
	v_sqrt_f32_e32 v129, v129
	s_nop 0
	v_mul_f32_e32 v196, v125, v129
	v_exp_f32_e32 v125, v131
	s_nop 0
	v_add_f32_e32 v125, 1.0, v125
	v_mul_f32_e32 v129, v125, v127
	v_rcp_f32_e32 v129, v129
	s_nop 0
	v_mul_f32_e32 v127, v127, v129
	v_mul_f32_e32 v127, v186, v127
	v_exp_f32_e32 v197, v127
	v_mul_f32_e32 v125, v125, v129
	v_mul_f32_e32 v124, v125, v124
	v_mul_f32_e32 v125, v132, v133
	v_fma_f32 v127, -v197, v197, 1.0
	v_sqrt_f32_e32 v127, v127
	v_mul_f32_e32 v125, v128, v125
	v_mul_f32_e32 v125, v126, v125
	v_mul_f32_e32 v198, v124, v127
	v_fma_f32 v124, v133, v32, v190
	v_fma_f32 v124, v128, v124, v193
	v_fma_f32 v124, v126, v124, v196
	ds_bpermute_b32 v127, v155, v125
	ds_bpermute_b32 v129, v155, v124
	s_waitcnt lgkmcnt(1)
; template <int PASS>
; __device__ __forceinline__ void rglru_phase(const Ctx& F, int l, const bf16_t* XRb, bf16_t* GRb, bool latent_only = false) {
;     ...
;             for (int mt = 0; mt < 4; ++mt) {
;                 f32x4 ag[4];
; #pragma unroll
;                 for (int gt = 0; gt < 4; ++gt) { const float nb = (gt & 1) ? nbx[gt >> 1] : nba[gt >> 1]; ag[gt] = (f32x4){nb, nb, nb, nb}; }
; #pragma unroll
;                 for (int ks = 0; ks < 4; ++ks) { const bf16x8 af = *(const LAS bf16x8*)(XT + (mt * 16 + l15) * XT_LD + ks * 32 + 8 * l4);
; #pragma unroll
;                     for (int gt = 0; gt < 4; ++gt) ag[gt] = __builtin_amdgcn_mfma_f32_16x16x32_bf16(af, Bf[gt][ks], ag[gt], 0, 0, 0); }
;                 float ea[2][4], eb[2][4];
; #pragma unroll
;                 for (int r = 0; r < 4; ++r) { const int tok = mt * 16 + 4 * l4 + r;
;                     const float xv = bf2f(XT[tok * XT_LD + cw + l15]);
; #pragma unroll
;                     for (int d = 0; d < 2; ++d) {
;                         const float e1 = 1.0f + __builtin_amdgcn_exp2f(ag[2 * d][r]), e2 = 1.0f + __builtin_amdgcn_exp2f(ag[2 * d + 1][r]);
;                         const float inv = __builtin_amdgcn_rcpf(e1 * e2); const float rgate = e2 * inv, igate = e1 * inv;
;                         const float a = __builtin_amdgcn_exp2f(rgate * cl2[d]);
;                         const float om = fmaf(-a, a, 1.0f);
;                         const float bv = __builtin_amdgcn_sqrtf(om) * (igate * xv);
;                         ea[d][r] = a; eb[d][r] = bv; } }
;     ...
;                         { const float Ap = BPF(lane - 16, A), Bp = BPF(lane - 16, B); if (l4 >= 1) { B = A * Bp + B; A = A * Ap; } }
;                         { const float Ap = BPF(lane - 32, A), Bp = BPF(lane - 32, B); if (l4 >= 2) { B = A * Bp + B; A = A * Ap; } }
;                         const float At = BPF(48 + l15, A), Bt = BPF(48 + l15, B);
;                         float Ae = BPF(lane - 16, A), Be = BPF(lane - 16, B); if (l4 == 0) { Ae = 1.f; Be = 0.f; }
;                         float h = Ae * hF + Be;
; #pragma unroll
;                         for (int r = 0; r < 4; ++r) { h = ea[0][r] * h + eb[0][r]; hfv[mt][r] = h; }
;                         hF = At * hF + Bt;
;                     }
;                     {
;                         float A = ea[1][3], B = eb[1][3];
; #pragma unroll
	v_mul_f32_e32 v127, v125, v127
	s_waitcnt lgkmcnt(0)
	v_fma_f32 v129, v125, v129, v124
	v_cndmask_b32_e64 v125, v125, v127, s[48:49]
	v_cndmask_b32_e64 v124, v124, v129, s[48:49]
	ds_bpermute_b32 v127, v156, v125
	ds_bpermute_b32 v129, v156, v124
	s_waitcnt lgkmcnt(1)
	v_mul_f32_e32 v127, v125, v127
	s_waitcnt lgkmcnt(0)
	v_fma_f32 v129, v125, v129, v124
	v_cndmask_b32_e64 v125, v125, v127, s[50:51]
	v_cndmask_b32_e64 v124, v124, v129, s[50:51]
	ds_bpermute_b32 v127, v158, v125
	ds_bpermute_b32 v225, v158, v124
	ds_bpermute_b32 v125, v155, v125
	ds_bpermute_b32 v124, v155, v124
	s_waitcnt lgkmcnt(2)
	v_fmac_f32_e32 v225, v201, v127
	s_waitcnt lgkmcnt(1)
	v_cndmask_b32_e64 v125, v125, 1.0, s[52:53]
	s_waitcnt lgkmcnt(0)
	v_cndmask_b32_e64 v124, v124, 0, s[52:53]
	v_fmac_f32_e32 v124, v201, v125
	v_fmac_f32_e32 v32, v132, v124
	v_fma_f32 v124, v194, v198, v195
	v_mul_f32_e32 v125, v197, v194
	v_fmac_f32_e32 v190, v133, v32
	v_fma_f32 v124, v191, v124, v192
	v_mul_f32_e32 v125, v191, v125
	v_fmac_f32_e32 v193, v128, v190
	v_fma_f32 v124, v188, v124, v189
	v_mul_f32_e32 v125, v188, v125
	v_fmac_f32_e32 v196, v126, v193
	ds_bpermute_b32 v126, v159, v125
	ds_bpermute_b32 v128, v159, v124
	s_waitcnt lgkmcnt(1)
	v_mul_f32_e32 v126, v125, v126
	s_waitcnt lgkmcnt(0)
	v_fma_f32 v128, v125, v128, v124
	v_cndmask_b32_e64 v125, v125, v126, s[54:55]
	v_cndmask_b32_e64 v124, v124, v128, s[54:55]
	ds_bpermute_b32 v126, v156, v125
	ds_bpermute_b32 v128, v156, v124
	s_waitcnt lgkmcnt(1)
	v_mul_f32_e32 v126, v125, v126
	s_waitcnt lgkmcnt(0)
	v_fma_f32 v128, v125, v128, v124
	v_cndmask_b32_e64 v125, v125, v126, s[56:57]
	v_cndmask_b32_e64 v124, v124, v128, s[56:57]
	ds_bpermute_b32 v125, v159, v125
	ds_bpermute_b32 v124, v159, v124
	s_waitcnt lgkmcnt(1)
	v_cndmask_b32_e64 v200, v125, 1.0, s[58:59]
	s_waitcnt lgkmcnt(0)
	v_cndmask_b32_e64 v199, v124, 0, s[58:59]
	ds_read_b128 v[124:127], v180 offset:4352
	s_waitcnt lgkmcnt(0)
	v_mfma_f32_16x16x32_bf16 v[128:131], v[124:127], v[0:3], v[100:103]
	v_mfma_f32_16x16x32_bf16 v[132:135], v[124:127], v[16:19], v[104:107]
	v_mfma_f32_16x16x32_bf16 v[136:139], v[124:127], v[36:39], v[108:111]
	v_mfma_f32_16x16x32_bf16 v[124:127], v[124:127], v[52:55], v[112:115]
	v_mfma_f32_16x16x32_bf16 v[128:131], v[160:163], v[4:7], v[128:131]
	v_mfma_f32_16x16x32_bf16 v[132:135], v[160:163], v[20:23], v[132:135]
	v_mfma_f32_16x16x32_bf16 v[136:139], v[160:163], v[40:43], v[136:139]
	v_mfma_f32_16x16x32_bf16 v[124:127], v[160:163], v[56:59], v[124:127]
	ds_read_b128 v[160:163], v180 offset:4480
	s_waitcnt lgkmcnt(0)
	v_mfma_f32_16x16x32_bf16 v[128:131], v[160:163], v[8:11], v[128:131]
	v_mfma_f32_16x16x32_bf16 v[132:135], v[160:163], v[24:27], v[132:135]
	v_mfma_f32_16x16x32_bf16 v[202:205], v[160:163], v[44:47], v[136:139]
	v_mfma_f32_16x16x32_bf16 v[124:127], v[160:163], v[60:63], v[124:127]
	ds_read_b128 v[160:163], v180 offset:4544
	s_waitcnt lgkmcnt(0)
	v_mfma_f32_16x16x32_bf16 v[136:139], v[160:163], v[12:15], v[128:131]
	s_nop 7
	v_exp_f32_e32 v136, v136
	v_mfma_f32_16x16x32_bf16 v[132:135], v[160:163], v[28:31], v[132:135]
	v_add_f32_e32 v136, 1.0, v136
	v_mfma_f32_16x16x32_bf16 v[128:131], v[160:163], v[48:51], v[202:205]
	v_mfma_f32_16x16x32_bf16 v[124:127], v[160:163], v[64:67], v[124:127]
	s_nop 4
	v_exp_f32_e32 v132, v132
	ds_read_u16 v160, v181 offset:4352
	v_exp_f32_e32 v128, v128
	v_exp_f32_e32 v133, v133
	v_add_f32_e32 v132, 1.0, v132
	v_mul_f32_e32 v161, v136, v132
	v_rcp_f32_e32 v161, v161
	v_exp_f32_e32 v124, v124
	s_waitcnt lgkmcnt(0)
	v_lshlrev_b32_e32 v160, 16, v160
	v_add_f32_e32 v128, 1.0, v128
	v_mul_f32_e32 v132, v132, v161
	v_mul_f32_e32 v132, v185, v132
	v_exp_f32_e32 v132, v132
	v_mul_f32_e32 v136, v136, v161
	v_mul_f32_e32 v136, v136, v160
	v_add_f32_e32 v124, 1.0, v124
	v_fma_f32 v161, -v132, v132, 1.0
	v_sqrt_f32_e32 v161, v161
	v_add_f32_e32 v133, 1.0, v133
	v_exp_f32_e32 v129, v129
	v_exp_f32_e32 v125, v125
	v_mul_f32_e32 v201, v136, v161
	v_mul_f32_e32 v136, v128, v124
	v_rcp_f32_e32 v136, v136
	v_add_f32_e32 v129, 1.0, v129
	v_add_f32_e32 v125, 1.0, v125
	v_exp_f32_e32 v126, v126
	v_mul_f32_e32 v124, v124, v136
	v_mul_f32_e32 v124, v186, v124
	v_exp_f32_e32 v202, v124
	v_mul_f32_e32 v128, v128, v136
	v_mul_f32_e32 v128, v128, v160
	v_add_f32_e32 v126, 1.0, v126
	v_fma_f32 v124, -v202, v202, 1.0
	v_sqrt_f32_e32 v124, v124
	v_exp_f32_e32 v127, v127
	ds_read_b128 v[160:163], v180 offset:8768
	v_mul_f32_e32 v203, v128, v124
	ds_read_u16 v124, v181 offset:4624
	v_add_f32_e32 v127, 1.0, v127
	s_waitcnt lgkmcnt(0)
	v_lshlrev_b32_e32 v128, 16, v124
	v_exp_f32_e32 v124, v137
	s_nop 0
	v_add_f32_e32 v124, 1.0, v124
	v_mul_f32_e32 v136, v124, v133
	v_rcp_f32_e32 v136, v136
	s_nop 0
	v_mul_f32_e32 v133, v133, v136
	v_mul_f32_e32 v136, v124, v136
	v_mul_f32_e32 v124, v185, v133
	v_exp_f32_e32 v124, v124
	v_mul_f32_e32 v136, v136, v128
	v_fma_f32 v133, -v124, v124, 1.0
	v_sqrt_f32_e32 v133, v133
	s_nop 0
	v_mul_f32_e32 v204, v136, v133
	v_mul_f32_e32 v133, v129, v125
	v_rcp_f32_e32 v133, v133
	s_nop 0
	v_mul_f32_e32 v125, v125, v133
	v_mul_f32_e32 v125, v186, v125
	v_exp_f32_e32 v205, v125
	v_mul_f32_e32 v129, v129, v133
	v_mul_f32_e32 v128, v129, v128
	v_exp_f32_e32 v129, v134
	v_fma_f32 v125, -v205, v205, 1.0
	v_sqrt_f32_e32 v125, v125
	v_add_f32_e32 v129, 1.0, v129
	v_mul_f32_e32 v206, v128, v125
	ds_read_u16 v125, v181 offset:4896
	s_waitcnt lgkmcnt(0)
; template <int PASS>
; __device__ __forceinline__ void rglru_phase(const Ctx& F, int l, const bf16_t* XRb, bf16_t* GRb, bool latent_only = false) {
;     ...
;             for (int mt = 0; mt < 4; ++mt) {
;                 f32x4 ag[4];
; #pragma unroll
;                 for (int gt = 0; gt < 4; ++gt) { const float nb = (gt & 1) ? nbx[gt >> 1] : nba[gt >> 1]; ag[gt] = (f32x4){nb, nb, nb, nb}; }
; #pragma unroll
;                 for (int ks = 0; ks < 4; ++ks) { const bf16x8 af = *(const LAS bf16x8*)(XT + (mt * 16 + l15) * XT_LD + ks * 32 + 8 * l4);
; #pragma unroll
;                     for (int gt = 0; gt < 4; ++gt) ag[gt] = __builtin_amdgcn_mfma_f32_16x16x32_bf16(af, Bf[gt][ks], ag[gt], 0, 0, 0); }
;                 float ea[2][4], eb[2][4];
; #pragma unroll
;                 for (int r = 0; r < 4; ++r) { const int tok = mt * 16 + 4 * l4 + r;
;                     const float xv = bf2f(XT[tok * XT_LD + cw + l15]);
; #pragma unroll
;                     for (int d = 0; d < 2; ++d) {
;                         const float e1 = 1.0f + __builtin_amdgcn_exp2f(ag[2 * d][r]), e2 = 1.0f + __builtin_amdgcn_exp2f(ag[2 * d + 1][r]);
;                         const float inv = __builtin_amdgcn_rcpf(e1 * e2); const float rgate = e2 * inv, igate = e1 * inv;
;                         const float a = __builtin_amdgcn_exp2f(rgate * cl2[d]);
;                         const float om = fmaf(-a, a, 1.0f);
;                         const float bv = __builtin_amdgcn_sqrtf(om) * (igate * xv);
;                         ea[d][r] = a; eb[d][r] = bv; } }
;     ...
;                         { const float Ap = BPF(lane - 16, A), Bp = BPF(lane - 16, B); if (l4 >= 1) { B = A * Bp + B; A = A * Ap; } }
;                         { const float Ap = BPF(lane - 32, A), Bp = BPF(lane - 32, B); if (l4 >= 2) { B = A * Bp + B; A = A * Ap; } }
;                         const float At = BPF(48 + l15, A), Bt = BPF(48 + l15, B);
;                         float Ae = BPF(lane - 16, A), Be = BPF(lane - 16, B); if (l4 == 0) { Ae = 1.f; Be = 0.f; }
;                         float h = Ae * hF + Be;
; #pragma unroll
;                         for (int r = 0; r < 4; ++r) { h = ea[0][r] * h + eb[0][r]; hfv[mt][r] = h; }
;                         hF = At * hF + Bt;
;                     }
;                     {
;                         float A = ea[1][3], B = eb[1][3];
; #pragma unroll
	v_lshlrev_b32_e32 v128, 16, v125
	v_exp_f32_e32 v125, v138
	s_nop 0
	v_add_f32_e32 v125, 1.0, v125
	v_mul_f32_e32 v133, v125, v129
	v_rcp_f32_e32 v133, v133
	s_nop 0
	v_mul_f32_e32 v129, v129, v133
	v_mul_f32_e32 v133, v125, v133
	v_mul_f32_e32 v125, v185, v129
	v_exp_f32_e32 v125, v125
	v_mul_f32_e32 v133, v133, v128
	v_fma_f32 v129, -v125, v125, 1.0
	v_sqrt_f32_e32 v129, v129
	s_nop 0
	v_mul_f32_e32 v207, v133, v129
	v_exp_f32_e32 v129, v130
	s_nop 0
	v_add_f32_e32 v129, 1.0, v129
	v_mul_f32_e32 v130, v129, v126
	v_rcp_f32_e32 v130, v130
	s_nop 0
	v_mul_f32_e32 v126, v126, v130
	v_mul_f32_e32 v126, v186, v126
	v_exp_f32_e32 v208, v126
	v_mul_f32_e32 v129, v129, v130
	v_mul_f32_e32 v128, v129, v128
	v_exp_f32_e32 v129, v135
	v_fma_f32 v126, -v208, v208, 1.0
	v_sqrt_f32_e32 v126, v126
	v_add_f32_e32 v129, 1.0, v129
	v_mul_f32_e32 v209, v128, v126
	v_exp_f32_e32 v128, v139
	ds_read_u16 v126, v181 offset:5168
	v_add_f32_e32 v128, 1.0, v128
	v_mul_f32_e32 v130, v128, v129
	v_rcp_f32_e32 v130, v130
	s_waitcnt lgkmcnt(0)
	v_lshlrev_b32_e32 v126, 16, v126
	v_mul_f32_e32 v129, v129, v130
	v_mul_f32_e32 v129, v185, v129
	v_exp_f32_e32 v129, v129
	v_mul_f32_e32 v128, v128, v130
	v_mul_f32_e32 v128, v128, v126
	v_fma_f32 v130, -v129, v129, 1.0
	v_sqrt_f32_e32 v130, v130
	s_nop 0
	v_mul_f32_e32 v210, v128, v130
	v_exp_f32_e32 v128, v131
	s_nop 0
	v_add_f32_e32 v128, 1.0, v128
	v_mul_f32_e32 v130, v128, v127
	v_rcp_f32_e32 v130, v130
	s_nop 0
	v_mul_f32_e32 v127, v127, v130
	v_mul_f32_e32 v127, v186, v127
	v_exp_f32_e32 v211, v127
	v_mul_f32_e32 v128, v128, v130
	v_mul_f32_e32 v126, v128, v126
	v_fma_f32 v127, -v211, v211, 1.0
	v_sqrt_f32_e32 v127, v127
	s_nop 0
	v_mul_f32_e32 v212, v126, v127
	v_fma_f32 v126, v124, v201, v204
	v_mul_f32_e32 v127, v132, v124
	v_fma_f32 v126, v125, v126, v207
	v_mul_f32_e32 v127, v125, v127
	v_fma_f32 v126, v129, v126, v210
	v_mul_f32_e32 v127, v129, v127
	ds_bpermute_b32 v128, v155, v127
	ds_bpermute_b32 v130, v155, v126
	s_waitcnt lgkmcnt(1)
	v_mul_f32_e32 v128, v127, v128
	s_waitcnt lgkmcnt(0)
	v_fma_f32 v130, v127, v130, v126
	v_cndmask_b32_e64 v127, v127, v128, s[48:49]
	v_cndmask_b32_e64 v126, v126, v130, s[48:49]
	ds_bpermute_b32 v128, v156, v127
	ds_bpermute_b32 v130, v156, v126
	s_waitcnt lgkmcnt(1)
	v_mul_f32_e32 v128, v127, v128
	s_waitcnt lgkmcnt(0)
	v_fma_f32 v130, v127, v130, v126
	v_cndmask_b32_e64 v127, v127, v128, s[50:51]
	v_cndmask_b32_e64 v126, v126, v130, s[50:51]
	ds_bpermute_b32 v128, v158, v127
	ds_bpermute_b32 v242, v158, v126
	ds_bpermute_b32 v127, v155, v127
	ds_bpermute_b32 v126, v155, v126
	s_waitcnt lgkmcnt(2)
	v_fmac_f32_e32 v242, v225, v128
	s_waitcnt lgkmcnt(1)
	v_cndmask_b32_e64 v127, v127, 1.0, s[52:53]
	s_waitcnt lgkmcnt(0)
	v_cndmask_b32_e64 v126, v126, 0, s[52:53]
	v_fmac_f32_e32 v126, v225, v127
	v_fmac_f32_e32 v201, v132, v126
	v_fmac_f32_e32 v204, v124, v201
	v_fmac_f32_e32 v207, v125, v204
	v_fma_f32 v124, v208, v212, v209
	v_mul_f32_e32 v125, v211, v208
	v_fma_f32 v124, v205, v124, v206
	v_mul_f32_e32 v125, v205, v125
	v_fma_f32 v124, v202, v124, v203
	v_mul_f32_e32 v125, v202, v125
	ds_bpermute_b32 v126, v159, v125
	ds_bpermute_b32 v127, v159, v124
	v_fmac_f32_e32 v210, v129, v207
	s_waitcnt lgkmcnt(1)
	v_mul_f32_e32 v126, v125, v126
	s_waitcnt lgkmcnt(0)
	v_fma_f32 v127, v125, v127, v124
	v_cndmask_b32_e64 v125, v125, v126, s[54:55]
	v_cndmask_b32_e64 v124, v124, v127, s[54:55]
	ds_bpermute_b32 v126, v156, v125
	ds_bpermute_b32 v127, v156, v124
	s_waitcnt lgkmcnt(1)
	v_mul_f32_e32 v126, v125, v126
	s_waitcnt lgkmcnt(0)
	v_fma_f32 v127, v125, v127, v124
	v_cndmask_b32_e64 v125, v125, v126, s[56:57]
	v_cndmask_b32_e64 v124, v124, v127, s[56:57]
	ds_bpermute_b32 v214, v157, v125
	ds_bpermute_b32 v213, v157, v124
	ds_bpermute_b32 v125, v159, v125
	ds_bpermute_b32 v124, v159, v124
	s_waitcnt lgkmcnt(1)
	v_cndmask_b32_e64 v224, v125, 1.0, s[58:59]
	s_waitcnt lgkmcnt(0)
	v_cndmask_b32_e64 v215, v124, 0, s[58:59]
	ds_read_b128 v[124:127], v180 offset:8704
	s_waitcnt lgkmcnt(0)
	v_mfma_f32_16x16x32_bf16 v[128:131], v[124:127], v[0:3], v[100:103]
	v_mfma_f32_16x16x32_bf16 v[132:135], v[124:127], v[16:19], v[104:107]
	v_mfma_f32_16x16x32_bf16 v[136:139], v[124:127], v[36:39], v[108:111]
	v_mfma_f32_16x16x32_bf16 v[124:127], v[124:127], v[52:55], v[112:115]
	v_mfma_f32_16x16x32_bf16 v[128:131], v[160:163], v[4:7], v[128:131]
	v_mfma_f32_16x16x32_bf16 v[132:135], v[160:163], v[20:23], v[132:135]
	v_mfma_f32_16x16x32_bf16 v[136:139], v[160:163], v[40:43], v[136:139]
	v_mfma_f32_16x16x32_bf16 v[124:127], v[160:163], v[56:59], v[124:127]
	ds_read_b128 v[160:163], v180 offset:8832
	s_waitcnt lgkmcnt(0)
	v_mfma_f32_16x16x32_bf16 v[128:131], v[160:163], v[8:11], v[128:131]
	v_mfma_f32_16x16x32_bf16 v[132:135], v[160:163], v[24:27], v[132:135]
	v_mfma_f32_16x16x32_bf16 v[220:223], v[160:163], v[44:47], v[136:139]
	v_mfma_f32_16x16x32_bf16 v[124:127], v[160:163], v[60:63], v[124:127]
	ds_read_b128 v[160:163], v180 offset:8896
	s_waitcnt lgkmcnt(0)
	v_mfma_f32_16x16x32_bf16 v[128:131], v[160:163], v[12:15], v[128:131]
	s_nop 7
	v_exp_f32_e32 v128, v128
	v_mfma_f32_16x16x32_bf16 v[136:139], v[160:163], v[28:31], v[132:135]
	v_add_f32_e32 v128, 1.0, v128
	v_mfma_f32_16x16x32_bf16 v[132:135], v[160:163], v[48:51], v[220:223]
	v_mfma_f32_16x16x32_bf16 v[124:127], v[160:163], v[64:67], v[124:127]
	s_nop 4
	v_exp_f32_e32 v136, v136
	ds_read_u16 v160, v181 offset:8704
	v_add_f32_e32 v136, 1.0, v136
	v_mul_f32_e32 v161, v128, v136
	v_rcp_f32_e32 v161, v161
	s_waitcnt lgkmcnt(0)
; template <int PASS>
; __device__ __forceinline__ void rglru_phase(const Ctx& F, int l, const bf16_t* XRb, bf16_t* GRb, bool latent_only = false) {
;     ...
;             for (int mt = 0; mt < 4; ++mt) {
;                 f32x4 ag[4];
; #pragma unroll
;                 for (int gt = 0; gt < 4; ++gt) { const float nb = (gt & 1) ? nbx[gt >> 1] : nba[gt >> 1]; ag[gt] = (f32x4){nb, nb, nb, nb}; }
; #pragma unroll
;                 for (int ks = 0; ks < 4; ++ks) { const bf16x8 af = *(const LAS bf16x8*)(XT + (mt * 16 + l15) * XT_LD + ks * 32 + 8 * l4);
; #pragma unroll
;                     for (int gt = 0; gt < 4; ++gt) ag[gt] = __builtin_amdgcn_mfma_f32_16x16x32_bf16(af, Bf[gt][ks], ag[gt], 0, 0, 0); }
;                 float ea[2][4], eb[2][4];
; #pragma unroll
;                 for (int r = 0; r < 4; ++r) { const int tok = mt * 16 + 4 * l4 + r;
;                     const float xv = bf2f(XT[tok * XT_LD + cw + l15]);
; #pragma unroll
;                     for (int d = 0; d < 2; ++d) {
;                         const float e1 = 1.0f + __builtin_amdgcn_exp2f(ag[2 * d][r]), e2 = 1.0f + __builtin_amdgcn_exp2f(ag[2 * d + 1][r]);
;                         const float inv = __builtin_amdgcn_rcpf(e1 * e2); const float rgate = e2 * inv, igate = e1 * inv;
;                         const float a = __builtin_amdgcn_exp2f(rgate * cl2[d]);
;                         const float om = fmaf(-a, a, 1.0f);
;                         const float bv = __builtin_amdgcn_sqrtf(om) * (igate * xv);
;                         ea[d][r] = a; eb[d][r] = bv; } }
;     ...
;                         { const float Ap = BPF(lane - 16, A), Bp = BPF(lane - 16, B); if (l4 >= 1) { B = A * Bp + B; A = A * Ap; } }
;                         { const float Ap = BPF(lane - 32, A), Bp = BPF(lane - 32, B); if (l4 >= 2) { B = A * Bp + B; A = A * Ap; } }
;                         const float At = BPF(48 + l15, A), Bt = BPF(48 + l15, B);
;                         float Ae = BPF(lane - 16, A), Be = BPF(lane - 16, B); if (l4 == 0) { Ae = 1.f; Be = 0.f; }
;                         float h = Ae * hF + Be;
; #pragma unroll
;                         for (int r = 0; r < 4; ++r) { h = ea[0][r] * h + eb[0][r]; hfv[mt][r] = h; }
;                         hF = At * hF + Bt;
;                     }
;                     {
;                         float A = ea[1][3], B = eb[1][3];
; #pragma unroll
	v_lshlrev_b32_e32 v160, 16, v160
	v_exp_f32_e32 v124, v124
	v_exp_f32_e32 v125, v125
	v_mul_f32_e32 v136, v136, v161
	v_mul_f32_e32 v136, v185, v136
	v_exp_f32_e32 v136, v136
	v_mul_f32_e32 v128, v128, v161
	v_mul_f32_e32 v128, v128, v160
	v_add_f32_e32 v124, 1.0, v124
	v_fma_f32 v161, -v136, v136, 1.0
	v_sqrt_f32_e32 v161, v161
	v_add_f32_e32 v125, 1.0, v125
	v_exp_f32_e32 v126, v126
	v_exp_f32_e32 v127, v127
	v_mul_f32_e32 v225, v128, v161
	v_exp_f32_e32 v128, v132
	v_add_f32_e32 v126, 1.0, v126
	v_add_f32_e32 v127, 1.0, v127
	v_add_f32_e32 v128, 1.0, v128
	v_mul_f32_e32 v132, v128, v124
	v_rcp_f32_e32 v132, v132
	s_nop 0
	v_mul_f32_e32 v124, v124, v132
	v_mul_f32_e32 v124, v186, v124
	v_exp_f32_e32 v226, v124
	v_mul_f32_e32 v128, v128, v132
	v_mul_f32_e32 v128, v128, v160
	ds_read_b128 v[160:163], v180 offset:13120
	v_fma_f32 v124, -v226, v226, 1.0
	v_sqrt_f32_e32 v124, v124
	s_nop 0
	v_mul_f32_e32 v227, v128, v124
	v_exp_f32_e32 v128, v129
	v_exp_f32_e32 v129, v137
	ds_read_u16 v124, v181 offset:8976
	v_add_f32_e32 v128, 1.0, v128
	v_add_f32_e32 v129, 1.0, v129
	v_mul_f32_e32 v132, v128, v129
	v_rcp_f32_e32 v132, v132
	s_waitcnt lgkmcnt(0)
	v_lshlrev_b32_e32 v124, 16, v124
	v_mul_f32_e32 v129, v129, v132
	v_mul_f32_e32 v129, v185, v129
	v_exp_f32_e32 v129, v129
	v_mul_f32_e32 v128, v128, v132
	v_mul_f32_e32 v128, v128, v124
	v_fma_f32 v132, -v129, v129, 1.0
	v_sqrt_f32_e32 v132, v132
	s_nop 0
	v_mul_f32_e32 v228, v128, v132
	v_exp_f32_e32 v128, v133
	s_nop 0
	v_add_f32_e32 v128, 1.0, v128
	v_mul_f32_e32 v132, v128, v125
	v_rcp_f32_e32 v132, v132
	s_nop 0
	v_mul_f32_e32 v125, v125, v132
	v_mul_f32_e32 v125, v186, v125
	v_exp_f32_e32 v229, v125
	v_mul_f32_e32 v128, v128, v132
	v_mul_f32_e32 v124, v128, v124
	v_exp_f32_e32 v128, v138
	v_fma_f32 v125, -v229, v229, 1.0
	v_sqrt_f32_e32 v125, v125
	v_add_f32_e32 v128, 1.0, v128
	v_mul_f32_e32 v230, v124, v125
	v_exp_f32_e32 v125, v130
	ds_read_u16 v124, v181 offset:9248
	v_add_f32_e32 v125, 1.0, v125
	v_mul_f32_e32 v130, v125, v128
	v_rcp_f32_e32 v130, v130
	s_waitcnt lgkmcnt(0)
	v_lshlrev_b32_e32 v124, 16, v124
	v_mul_f32_e32 v128, v128, v130
	v_mul_f32_e32 v128, v185, v128
	v_exp_f32_e32 v128, v128
	v_mul_f32_e32 v125, v125, v130
	v_mul_f32_e32 v125, v125, v124
	v_fma_f32 v130, -v128, v128, 1.0
	v_sqrt_f32_e32 v130, v130
	s_nop 0
	v_mul_f32_e32 v231, v125, v130
	v_exp_f32_e32 v125, v134
	s_nop 0
	v_add_f32_e32 v125, 1.0, v125
	v_mul_f32_e32 v130, v125, v126
	v_rcp_f32_e32 v130, v130
	s_nop 0
	v_mul_f32_e32 v126, v126, v130
	v_mul_f32_e32 v126, v186, v126
	v_exp_f32_e32 v232, v126
	v_mul_f32_e32 v125, v125, v130
	v_mul_f32_e32 v124, v125, v124
	v_exp_f32_e32 v125, v131
	v_fma_f32 v126, -v232, v232, 1.0
	v_sqrt_f32_e32 v126, v126
	v_add_f32_e32 v125, 1.0, v125
	v_mul_f32_e32 v233, v124, v126
	v_exp_f32_e32 v126, v139
	ds_read_u16 v124, v181 offset:9520
	v_add_f32_e32 v126, 1.0, v126
	v_mul_f32_e32 v130, v125, v126
	v_rcp_f32_e32 v130, v130
	s_waitcnt lgkmcnt(0)
	v_lshlrev_b32_e32 v124, 16, v124
	v_mul_f32_e32 v126, v126, v130
	v_mul_f32_e32 v126, v185, v126
	v_exp_f32_e32 v126, v126
	v_mul_f32_e32 v125, v125, v130
	v_mul_f32_e32 v125, v125, v124
	v_fma_f32 v130, -v126, v126, 1.0
	v_sqrt_f32_e32 v130, v130
	s_nop 0
	v_mul_f32_e32 v234, v125, v130
	v_exp_f32_e32 v125, v135
	s_nop 0
	v_add_f32_e32 v125, 1.0, v125
	v_mul_f32_e32 v130, v125, v127
	v_rcp_f32_e32 v130, v130
	s_nop 0
	v_mul_f32_e32 v127, v127, v130
	v_mul_f32_e32 v127, v186, v127
	v_exp_f32_e32 v235, v127
	v_mul_f32_e32 v125, v125, v130
	v_mul_f32_e32 v124, v125, v124
	v_mul_f32_e32 v125, v136, v129
	v_fma_f32 v127, -v235, v235, 1.0
	v_sqrt_f32_e32 v127, v127
	v_mul_f32_e32 v125, v128, v125
	v_mul_f32_e32 v125, v126, v125
	v_mul_f32_e32 v236, v124, v127
	v_fma_f32 v124, v129, v225, v228
	v_fma_f32 v124, v128, v124, v231
	v_fma_f32 v124, v126, v124, v234
	ds_bpermute_b32 v127, v155, v125
	ds_bpermute_b32 v130, v155, v124
	s_waitcnt lgkmcnt(1)
	v_mul_f32_e32 v127, v125, v127
	s_waitcnt lgkmcnt(0)
	v_fma_f32 v130, v125, v130, v124
	v_cndmask_b32_e64 v125, v125, v127, s[48:49]
	v_cndmask_b32_e64 v124, v124, v130, s[48:49]
	ds_bpermute_b32 v127, v156, v125
	ds_bpermute_b32 v130, v156, v124
	s_waitcnt lgkmcnt(1)
	v_mul_f32_e32 v127, v125, v127
	s_waitcnt lgkmcnt(0)
	v_fma_f32 v130, v125, v130, v124
	v_cndmask_b32_e64 v125, v125, v127, s[50:51]
	v_cndmask_b32_e64 v124, v124, v130, s[50:51]
	ds_bpermute_b32 v127, v158, v125
	ds_bpermute_b32 v241, v158, v124
	ds_bpermute_b32 v125, v155, v125
	ds_bpermute_b32 v124, v155, v124
	s_waitcnt lgkmcnt(2)
	v_fmac_f32_e32 v241, v242, v127
	s_waitcnt lgkmcnt(1)
	v_cndmask_b32_e64 v125, v125, 1.0, s[52:53]
	s_waitcnt lgkmcnt(0)
	v_cndmask_b32_e64 v124, v124, 0, s[52:53]
	v_fmac_f32_e32 v124, v242, v125
	v_fmac_f32_e32 v225, v136, v124
	v_fma_f32 v124, v232, v236, v233
	v_mul_f32_e32 v125, v235, v232
	v_fmac_f32_e32 v228, v129, v225
	v_fma_f32 v124, v229, v124, v230
	v_mul_f32_e32 v125, v229, v125
	v_fmac_f32_e32 v231, v128, v228
	v_fma_f32 v124, v226, v124, v227
	v_mul_f32_e32 v125, v226, v125
	v_fmac_f32_e32 v234, v126, v231
	ds_bpermute_b32 v126, v159, v125
	ds_bpermute_b32 v128, v159, v124
	s_waitcnt lgkmcnt(1)
	v_mul_f32_e32 v126, v125, v126
	s_waitcnt lgkmcnt(0)
	v_fma_f32 v128, v125, v128, v124
	v_cndmask_b32_e64 v125, v125, v126, s[54:55]
	v_cndmask_b32_e64 v124, v124, v128, s[54:55]
	ds_bpermute_b32 v126, v156, v125
	ds_bpermute_b32 v128, v156, v124
	s_waitcnt lgkmcnt(1)
	v_mul_f32_e32 v126, v125, v126
	s_waitcnt lgkmcnt(0)
	v_fma_f32 v128, v125, v128, v124
	v_cndmask_b32_e64 v125, v125, v126, s[56:57]
	v_cndmask_b32_e64 v124, v124, v128, s[56:57]
	ds_bpermute_b32 v238, v157, v125
	ds_bpermute_b32 v237, v157, v124
	ds_bpermute_b32 v125, v159, v125
	ds_bpermute_b32 v124, v159, v124
	s_waitcnt lgkmcnt(1)
; #define LAS __attribute__((address_space(3)))
; __device__ __forceinline__ float bf2f(unsigned short v) { return __uint_as_float(((unsigned)v) << 16); }
; template <int PASS>
; __device__ __forceinline__ void rglru_phase(const Ctx& F, int l, const bf16_t* XRb, bf16_t* GRb, bool latent_only = false) {
;     ...
;             for (int mt = 0; mt < 4; ++mt) {
;                 f32x4 ag[4];
; #pragma unroll
;                 for (int gt = 0; gt < 4; ++gt) { const float nb = (gt & 1) ? nbx[gt >> 1] : nba[gt >> 1]; ag[gt] = (f32x4){nb, nb, nb, nb}; }
; #pragma unroll
;                 for (int ks = 0; ks < 4; ++ks) { const bf16x8 af = *(const LAS bf16x8*)(XT + (mt * 16 + l15) * XT_LD + ks * 32 + 8 * l4);
; #pragma unroll
;                     for (int gt = 0; gt < 4; ++gt) ag[gt] = __builtin_amdgcn_mfma_f32_16x16x32_bf16(af, Bf[gt][ks], ag[gt], 0, 0, 0); }
;                 float ea[2][4], eb[2][4];
; #pragma unroll
;                 for (int r = 0; r < 4; ++r) { const int tok = mt * 16 + 4 * l4 + r;
;                     const float xv = bf2f(XT[tok * XT_LD + cw + l15]);
; #pragma unroll
;                     for (int d = 0; d < 2; ++d) {
;                         const float e1 = 1.0f + __builtin_amdgcn_exp2f(ag[2 * d][r]), e2 = 1.0f + __builtin_amdgcn_exp2f(ag[2 * d + 1][r]);
;                         const float inv = __builtin_amdgcn_rcpf(e1 * e2); const float rgate = e2 * inv, igate = e1 * inv;
;                         const float a = __builtin_amdgcn_exp2f(rgate * cl2[d]);
;                         const float om = fmaf(-a, a, 1.0f);
;                         const float bv = __builtin_amdgcn_sqrtf(om) * (igate * xv);
;                         ea[d][r] = a; eb[d][r] = bv; } }
;     ...
;                         float A = ea[0][0], B = eb[0][0];
; #pragma unroll
;                         for (int r = 1; r < 4; ++r) { B = ea[0][r] * B + eb[0][r]; A *= ea[0][r]; }
	v_cndmask_b32_e64 v240, v125, 1.0, s[58:59]
	s_waitcnt lgkmcnt(0)
	v_cndmask_b32_e64 v239, v124, 0, s[58:59]
	ds_read_b128 v[124:127], v180 offset:13056
	s_waitcnt lgkmcnt(0)
	v_mfma_f32_16x16x32_bf16 v[128:131], v[124:127], v[0:3], v[100:103]
	v_mfma_f32_16x16x32_bf16 v[132:135], v[124:127], v[16:19], v[104:107]
	v_mfma_f32_16x16x32_bf16 v[136:139], v[124:127], v[36:39], v[108:111]
	v_mfma_f32_16x16x32_bf16 v[124:127], v[124:127], v[52:55], v[112:115]
	v_mfma_f32_16x16x32_bf16 v[128:131], v[160:163], v[4:7], v[128:131]
	v_mfma_f32_16x16x32_bf16 v[132:135], v[160:163], v[20:23], v[132:135]
	v_mfma_f32_16x16x32_bf16 v[136:139], v[160:163], v[40:43], v[136:139]
	v_mfma_f32_16x16x32_bf16 v[124:127], v[160:163], v[56:59], v[124:127]
	ds_read_b128 v[160:163], v180 offset:13184
	s_waitcnt lgkmcnt(0)
	v_mfma_f32_16x16x32_bf16 v[128:131], v[160:163], v[8:11], v[128:131]
	v_mfma_f32_16x16x32_bf16 v[132:135], v[160:163], v[24:27], v[132:135]
	v_mfma_f32_16x16x32_bf16 v[220:223], v[160:163], v[44:47], v[136:139]
	v_mfma_f32_16x16x32_bf16 v[124:127], v[160:163], v[60:63], v[124:127]
	ds_read_b128 v[160:163], v180 offset:13248
	s_waitcnt lgkmcnt(0)
	v_mfma_f32_16x16x32_bf16 v[136:139], v[160:163], v[12:15], v[128:131]
	s_nop 7
	v_exp_f32_e32 v136, v136
	v_mfma_f32_16x16x32_bf16 v[132:135], v[160:163], v[28:31], v[132:135]
	v_exp_f32_e32 v137, v137
	v_exp_f32_e32 v138, v138
	v_add_f32_e32 v136, 1.0, v136
	v_mfma_f32_16x16x32_bf16 v[128:131], v[160:163], v[48:51], v[220:223]
	v_add_f32_e32 v137, 1.0, v137
	s_nop 2
	v_exp_f32_e32 v132, v132
	v_exp_f32_e32 v133, v133
	v_mfma_f32_16x16x32_bf16 v[124:127], v[160:163], v[64:67], v[124:127]
	ds_read_u16 v160, v181 offset:13056
	v_add_f32_e32 v132, 1.0, v132
	v_mul_f32_e32 v161, v136, v132
	v_rcp_f32_e32 v161, v161
	v_exp_f32_e32 v128, v128
	s_nop 2
	v_exp_f32_e32 v124, v124
	s_waitcnt lgkmcnt(0)
	v_lshlrev_b32_e32 v160, 16, v160
	v_mul_f32_e32 v132, v132, v161
	v_mul_f32_e32 v132, v185, v132
	v_mul_f32_e32 v161, v136, v161
	v_exp_f32_e32 v136, v132
	v_mul_f32_e32 v161, v161, v160
	v_add_f32_e32 v128, 1.0, v128
	v_add_f32_e32 v124, 1.0, v124
	v_fma_f32 v132, -v136, v136, 1.0
	v_sqrt_f32_e32 v132, v132
	v_add_f32_e32 v133, 1.0, v133
	v_exp_f32_e32 v129, v129
	v_exp_f32_e32 v125, v125
	v_mul_f32_e32 v132, v161, v132
	v_mul_f32_e32 v161, v128, v124
	v_rcp_f32_e32 v161, v161
	v_add_f32_e32 v129, 1.0, v129
	v_add_f32_e32 v125, 1.0, v125
	v_exp_f32_e32 v134, v134
	v_mul_f32_e32 v124, v124, v161
	v_mul_f32_e32 v124, v186, v124
	v_exp_f32_e32 v124, v124
	v_mul_f32_e32 v128, v128, v161
	v_mul_f32_e32 v128, v128, v160
	ds_read_u16 v160, v181 offset:13328
	v_fma_f32 v161, -v124, v124, 1.0
	v_sqrt_f32_e32 v161, v161
	v_add_f32_e32 v138, 1.0, v138
	v_add_f32_e32 v134, 1.0, v134
	s_waitcnt lgkmcnt(0)
	v_lshlrev_b32_e32 v160, 16, v160
	v_mul_f32_e32 v128, v128, v161
	v_mul_f32_e32 v161, v137, v133
	v_rcp_f32_e32 v161, v161
	v_exp_f32_e32 v130, v130
	v_exp_f32_e32 v126, v126
	v_exp_f32_e32 v139, v139
	v_mul_f32_e32 v133, v133, v161
	v_mul_f32_e32 v133, v185, v133
	v_mul_f32_e32 v161, v137, v161
	v_exp_f32_e32 v137, v133
	v_mul_f32_e32 v161, v161, v160
	v_add_f32_e32 v130, 1.0, v130
	v_add_f32_e32 v126, 1.0, v126
	v_fma_f32 v133, -v137, v137, 1.0
	v_sqrt_f32_e32 v133, v133
	v_exp_f32_e32 v135, v135
	v_add_f32_e32 v139, 1.0, v139
	v_exp_f32_e32 v131, v131
	v_mul_f32_e32 v133, v161, v133
	v_mul_f32_e32 v161, v129, v125
	v_rcp_f32_e32 v161, v161
	v_add_f32_e32 v135, 1.0, v135
	v_exp_f32_e32 v127, v127
	v_add_f32_e32 v131, 1.0, v131
	v_mul_f32_e32 v125, v125, v161
	v_mul_f32_e32 v125, v186, v125
	v_exp_f32_e32 v125, v125
	v_mul_f32_e32 v129, v129, v161
	v_mul_f32_e32 v129, v129, v160
	ds_read_u16 v160, v181 offset:13600
	v_fma_f32 v161, -v125, v125, 1.0
	v_sqrt_f32_e32 v161, v161
	v_add_f32_e32 v127, 1.0, v127
	s_waitcnt lgkmcnt(0)
	v_lshlrev_b32_e32 v160, 16, v160
	v_mul_f32_e32 v129, v129, v161
	v_mul_f32_e32 v161, v138, v134
	v_rcp_f32_e32 v161, v161
	s_nop 0
	v_mul_f32_e32 v134, v134, v161
	v_mul_f32_e32 v134, v185, v134
	v_mul_f32_e32 v161, v138, v161
	v_exp_f32_e32 v138, v134
	v_mul_f32_e32 v161, v161, v160
	v_fma_f32 v134, -v138, v138, 1.0
	v_sqrt_f32_e32 v134, v134
	s_nop 0
	v_mul_f32_e32 v134, v161, v134
	v_mul_f32_e32 v161, v130, v126
	v_rcp_f32_e32 v161, v161
	s_nop 0
	v_mul_f32_e32 v130, v130, v161
	v_mul_f32_e32 v130, v130, v160
	ds_read_u16 v160, v181 offset:13872
	v_mul_f32_e32 v126, v126, v161
	v_mul_f32_e32 v126, v186, v126
	v_exp_f32_e32 v126, v126
	s_waitcnt lgkmcnt(0)
	s_waitcnt lgkmcnt(0)
	v_lshlrev_b32_e32 v242, 16, v160
	v_mul_f32_e32 v160, v139, v135
	v_rcp_f32_e32 v160, v160
	v_fma_f32 v161, -v126, v126, 1.0
	v_sqrt_f32_e32 v161, v161
	v_mul_f32_e32 v135, v135, v160
	v_mul_f32_e32 v135, v185, v135
	v_exp_f32_e32 v135, v135
	v_mul_f32_e32 v139, v139, v160
	v_mul_f32_e32 v139, v139, v242
	v_mul_f32_e32 v130, v130, v161
	v_fma_f32 v160, -v135, v135, 1.0
	v_sqrt_f32_e32 v160, v160
	v_mul_f32_e32 v161, v136, v137
	v_mul_f32_e32 v161, v138, v161
	v_mul_f32_e32 v161, v135, v161
	v_mul_f32_e32 v139, v139, v160
	v_mul_f32_e32 v160, v131, v127
	v_rcp_f32_e32 v160, v160
	ds_bpermute_b32 v162, v155, v161
	v_mul_f32_e32 v127, v127, v160
	v_mul_f32_e32 v127, v186, v127
	v_exp_f32_e32 v127, v127
	v_mul_f32_e32 v131, v131, v160
	v_mul_f32_e32 v131, v131, v242
	s_waitcnt lgkmcnt(0)
	v_mul_f32_e32 v162, v161, v162
	v_fma_f32 v160, -v127, v127, 1.0
	v_sqrt_f32_e32 v160, v160
	s_nop 0
	v_mul_f32_e32 v131, v131, v160
	v_fma_f32 v160, v137, v132, v133
	v_fma_f32 v160, v138, v160, v134
	v_fma_f32 v160, v135, v160, v139
	ds_bpermute_b32 v163, v155, v160
	s_waitcnt lgkmcnt(0)
; __device__ __forceinline__ float bflo(unsigned w) { return __uint_as_float(w << 16); }
; __device__ __forceinline__ float bfhi(unsigned w) { return __uint_as_float(w & 0xffff0000u); }
; #define BPF(src_, v_) __uint_as_float(__builtin_amdgcn_ds_bpermute(((src_) & 63) << 2, __float_as_uint(v_)))
; template <int PASS>
; __device__ __forceinline__ void rglru_phase(const Ctx& F, int l, const bf16_t* XRb, bf16_t* GRb, bool latent_only = false) {
;     ...
;                         { const float Ap = BPF(lane + 16, A), Bp = BPF(lane + 16, B); if (l4 <= 2) { B = A * Bp + B; A = A * Ap; } }
;                         { const float Ap = BPF(lane + 32, A), Bp = BPF(lane + 32, B); if (l4 <= 1) { B = A * Bp + B; A = A * Ap; } }
;                         bAt[mt] = BPF(l15, A); bBt[mt] = BPF(l15, B);
;                         float Ae = BPF(lane + 16, A), Be = BPF(lane + 16, B); if (l4 == 3) { Ae = 1.f; Be = 0.f; }
;                         bAe[mt] = Ae; bBe[mt] = Be;
; #pragma unroll
;                         for (int r = 0; r < 4; ++r) { ba_[mt][r] = ea[1][r]; bb_[mt][r] = eb[1][r]; }
;                     }
;                 }
;             }
;             if (PASS == 1) { if (lane < 16) { AGG[((size_t)(b * 2 + 0) * NCH + c) * 1024 + ch] = (f32x2){aggA[0], aggB[0]}; AGG[((size_t)(b * 2 + 1) * NCH + c) * 1024 + ch] = (f32x2){aggA[1], aggB[1]}; } }
;             asm volatile("s_waitcnt lgkmcnt(0)" ::: "memory"); __builtin_amdgcn_wave_barrier();
;             if (PASS == 2) {
;                 float hB = CAR[(1 * 9 + (c - c0)) * 16 + l15];
; #pragma unroll
;     ...
; #pragma unroll
;                     for (int r = 3; r >= 0; --r) { h = ba_[mt][r] * h + bb_[mt][r]; SCF[(r + 4 * mt + 16 * l4) * 17 + l15] = hfv[mt][r] + h; }
;                     hB = bAt[mt] * hB + bBt[mt]; }
;                 asm volatile("s_waitcnt lgkmcnt(0)" ::: "memory"); __builtin_amdgcn_wave_barrier();
;                 const size_t go = (size_t)(seg_row0 + tl0 + lane) * 1024 + blk * 128 + cw;
;                 float u[16];
;                 const int pl = (lane & 3) + 4 * (lane >> 4) + 16 * ((lane >> 2) & 3);
; #pragma unroll
;                 for (int e = 0; e < 16; ++e) { const float hs = SCF[pl * 17 + e]; const unsigned gw = e < 8 ? g0[e >> 1] : g1[(e - 8) >> 1];
;                     u[e] = hs * gelu_tanh((e & 1) ? bfhi(gw) : bflo(gw)); }
	v_fma_f32 v163, v161, v163, v160
	v_cndmask_b32_e64 v161, v161, v162, s[48:49]
	v_cndmask_b32_e64 v160, v160, v163, s[48:49]
	ds_bpermute_b32 v162, v156, v161
	ds_bpermute_b32 v163, v156, v160
	s_waitcnt lgkmcnt(1)
	v_mul_f32_e32 v162, v161, v162
	s_waitcnt lgkmcnt(0)
	v_fma_f32 v163, v161, v163, v160
	v_cndmask_b32_e64 v161, v161, v162, s[50:51]
	v_cndmask_b32_e64 v160, v160, v163, s[50:51]
	ds_bpermute_b32 v161, v155, v161
	ds_bpermute_b32 v160, v155, v160
	s_waitcnt lgkmcnt(1)
	v_cndmask_b32_e64 v161, v161, 1.0, s[52:53]
	s_waitcnt lgkmcnt(0)
	v_cndmask_b32_e64 v160, v160, 0, s[52:53]
	v_fmac_f32_e32 v160, v241, v161
	v_fmac_f32_e32 v132, v136, v160
	v_fmac_f32_e32 v133, v137, v132
	v_fmac_f32_e32 v134, v138, v133
	v_fmac_f32_e32 v139, v135, v134
	v_fma_f32 v135, v126, v131, v130
	v_mul_f32_e32 v136, v127, v126
	v_fma_f32 v135, v125, v135, v129
	v_mul_f32_e32 v136, v125, v136
	v_fma_f32 v135, v124, v135, v128
	v_mul_f32_e32 v136, v124, v136
	ds_bpermute_b32 v137, v159, v136
	ds_bpermute_b32 v138, v159, v135
	ds_read_b32 v160, v187 offset:576
	v_add_u32_e32 v187, 64, v187
	s_waitcnt lgkmcnt(2)
	v_mul_f32_e32 v137, v136, v137
	s_waitcnt lgkmcnt(1)
	v_fma_f32 v138, v136, v138, v135
	v_cndmask_b32_e64 v136, v136, v137, s[54:55]
	v_cndmask_b32_e64 v135, v135, v138, s[54:55]
	ds_bpermute_b32 v137, v156, v136
	ds_bpermute_b32 v138, v156, v135
	s_waitcnt lgkmcnt(1)
	v_mul_f32_e32 v137, v136, v137
	s_waitcnt lgkmcnt(0)
	v_fma_f32 v138, v136, v138, v135
	v_cndmask_b32_e64 v136, v136, v137, s[56:57]
	v_cndmask_b32_e64 v135, v135, v138, s[56:57]
	ds_bpermute_b32 v137, v157, v136
	ds_bpermute_b32 v138, v157, v135
	ds_bpermute_b32 v136, v159, v136
	ds_bpermute_b32 v135, v159, v135
	s_waitcnt lgkmcnt(2)
	v_fmac_f32_e32 v138, v160, v137
	s_waitcnt lgkmcnt(1)
	v_cndmask_b32_e64 v136, v136, 1.0, s[58:59]
	s_waitcnt lgkmcnt(0)
	v_cndmask_b32_e64 v135, v135, 0, s[58:59]
	v_fmac_f32_e32 v135, v136, v160
	v_fmac_f32_e32 v131, v127, v135
	v_fmac_f32_e32 v130, v126, v131
	v_fmac_f32_e32 v239, v240, v138
	v_fmac_f32_e32 v129, v125, v130
	v_fmac_f32_e32 v236, v235, v239
	v_fmac_f32_e32 v237, v138, v238
	v_add_f32_e32 v127, v139, v131
	v_add_f32_e32 v126, v134, v130
	v_fmac_f32_e32 v128, v124, v129
	v_fmac_f32_e32 v233, v232, v236
	v_fmac_f32_e32 v215, v224, v237
	ds_write_b32 v182, v127 offset:20480
	ds_write_b32 v183, v126 offset:21432
	v_add_f32_e32 v125, v133, v129
	v_add_f32_e32 v124, v132, v128
	v_add_u32_e32 v126, 0x5000, v183
	v_fmac_f32_e32 v230, v229, v233
	v_fmac_f32_e32 v212, v211, v215
	v_fmac_f32_e32 v213, v237, v214
	ds_write2_b32 v126, v124, v125 offset0:204 offset1:221
	v_add_f32_e32 v124, v234, v236
	v_add_f32_e32 v125, v231, v233
	v_fmac_f32_e32 v227, v226, v230
	v_fmac_f32_e32 v209, v208, v212
	v_fmac_f32_e32 v199, v200, v213
	ds_write2_b32 v126, v125, v124 offset0:170 offset1:187
	v_add_f32_e32 v124, v228, v230
	v_add_f32_e32 v125, v225, v227
	v_fmac_f32_e32 v206, v205, v209
	v_fmac_f32_e32 v198, v197, v199
	ds_write2_b32 v126, v125, v124 offset0:136 offset1:153
	v_add_f32_e32 v124, v210, v212
	v_add_f32_e32 v125, v207, v209
	v_fmac_f32_e32 v203, v202, v206
	v_fmac_f32_e32 v195, v194, v198
	ds_write2_b32 v126, v125, v124 offset0:102 offset1:119
	v_add_f32_e32 v124, v204, v206
	v_add_f32_e32 v125, v201, v203
	v_fmac_f32_e32 v192, v191, v195
	ds_write2_b32 v126, v125, v124 offset0:68 offset1:85
	v_add_f32_e32 v124, v196, v198
	v_add_f32_e32 v125, v193, v195
	v_fmac_f32_e32 v189, v188, v192
	ds_write2_b32 v126, v125, v124 offset0:34 offset1:51
	v_add_f32_e32 v124, v190, v192
	v_add_f32_e32 v32, v32, v189
	ds_write2_b32 v126, v32, v124 offset1:17
	v_add_u32_e32 v135, 0x5000, v184
	s_waitcnt lgkmcnt(0)
	ds_read2_b32 v[188:189], v135 offset0:0 offset1:1
	ds_read2_b32 v[190:191], v135 offset0:2 offset1:3
	ds_read2_b32 v[192:193], v135 offset0:4 offset1:5
	ds_read2_b32 v[194:195], v135 offset0:6 offset1:7
	ds_read2_b32 v[196:197], v135 offset0:8 offset1:9
	ds_read2_b32 v[198:199], v135 offset0:10 offset1:11
	ds_read2_b32 v[200:201], v135 offset0:12 offset1:13
	ds_read2_b32 v[202:203], v135 offset0:14 offset1:15
	v_mov_b32_e32 v240, 0x3d372713
	v_mov_b32_e32 v160, 0x3f4c422a
	v_mov_b32_e32 v162, 0x3fb8aa3b
	s_waitcnt vmcnt(0)
	v_lshlrev_b32_e32 v204, 16, v120
	v_and_b32_e32 v205, 0xffff0000, v120
	v_lshlrev_b32_e32 v206, 16, v121
	v_and_b32_e32 v207, 0xffff0000, v121
	v_lshlrev_b32_e32 v208, 16, v122
	v_and_b32_e32 v209, 0xffff0000, v122
	v_lshlrev_b32_e32 v210, 16, v123
	v_and_b32_e32 v211, 0xffff0000, v123
	v_lshlrev_b32_e32 v212, 16, v116
	v_and_b32_e32 v213, 0xffff0000, v116
	v_lshlrev_b32_e32 v214, 16, v117
	v_and_b32_e32 v215, 0xffff0000, v117
	v_lshlrev_b32_e32 v220, 16, v118
	v_and_b32_e32 v221, 0xffff0000, v118
	v_lshlrev_b32_e32 v222, 16, v119
	v_and_b32_e32 v223, 0xffff0000, v119
	v_pk_mul_f32 v[224:225], v[204:205], v[240:241] op_sel_hi:[1,0]
	v_pk_mul_f32 v[226:227], v[206:207], v[240:241] op_sel_hi:[1,0]
	v_pk_mul_f32 v[228:229], v[208:209], v[240:241] op_sel_hi:[1,0]
	v_pk_mul_f32 v[230:231], v[210:211], v[240:241] op_sel_hi:[1,0]
	v_pk_mul_f32 v[232:233], v[212:213], v[240:241] op_sel_hi:[1,0]
	v_pk_mul_f32 v[234:235], v[214:215], v[240:241] op_sel_hi:[1,0]
	v_pk_mul_f32 v[236:237], v[220:221], v[240:241] op_sel_hi:[1,0]
	v_pk_mul_f32 v[238:239], v[222:223], v[240:241] op_sel_hi:[1,0]
	v_pk_mul_f32 v[224:225], v[224:225], v[204:205]
	v_pk_mul_f32 v[226:227], v[226:227], v[206:207]
	v_pk_mul_f32 v[228:229], v[228:229], v[208:209]
	v_pk_mul_f32 v[230:231], v[230:231], v[210:211]
	v_pk_mul_f32 v[232:233], v[232:233], v[212:213]
	v_pk_mul_f32 v[234:235], v[234:235], v[214:215]
	v_pk_mul_f32 v[236:237], v[236:237], v[220:221]
; __device__ __forceinline__ unsigned cvt_pk_bf16(float lo, float hi) { unsigned r; asm volatile("v_cvt_pk_bf16_f32 %0, %1, %2" : "=v"(r) : "v"(lo), "v"(hi)); return r; }
; __device__ __forceinline__ float bflo(unsigned w) { return __uint_as_float(w << 16); }
; __device__ __forceinline__ float bfhi(unsigned w) { return __uint_as_float(w & 0xffff0000u); }
; __device__ __forceinline__ float gelu_tanh(float x) { const float u = 0.7978845608028654f * (x + 0.044715f * x * x * x); const float t = 1.0f - 2.0f * __builtin_amdgcn_rcpf(1.0f + __expf(2.0f * u)); return 0.5f * x * (1.0f + t); }
; template <int PASS>
; __device__ __forceinline__ void rglru_phase(const Ctx& F, int l, const bf16_t* XRb, bf16_t* GRb, bool latent_only = false) {
;     ...
;                 float u[16];
;                 const int pl = (lane & 3) + 4 * (lane >> 4) + 16 * ((lane >> 2) & 3);
; #pragma unroll
;                 for (int e = 0; e < 16; ++e) { const float hs = SCF[pl * 17 + e]; const unsigned gw = e < 8 ? g0[e >> 1] : g1[(e - 8) >> 1];
;                     u[e] = hs * gelu_tanh((e & 1) ? bfhi(gw) : bflo(gw)); }
;                 u32x4 o0, o1; o0.x = cvt_pk_bf16(u[0], u[1]); o0.y = cvt_pk_bf16(u[2], u[3]); o0.z = cvt_pk_bf16(u[4], u[5]); o0.w = cvt_pk_bf16(u[6], u[7]);
;                 o1.x = cvt_pk_bf16(u[8], u[9]); o1.y = cvt_pk_bf16(u[10], u[11]); o1.z = cvt_pk_bf16(u[12], u[13]); o1.w = cvt_pk_bf16(u[14], u[15]);
;                 *(u32x4*)(GRb + go) = o0; *(u32x4*)(GRb + go + 8) = o1;
	v_pk_mul_f32 v[238:239], v[238:239], v[222:223]
	v_pk_fma_f32 v[224:225], v[224:225], v[204:205], v[204:205]
	v_pk_fma_f32 v[226:227], v[226:227], v[206:207], v[206:207]
	v_pk_fma_f32 v[228:229], v[228:229], v[208:209], v[208:209]
	v_pk_fma_f32 v[230:231], v[230:231], v[210:211], v[210:211]
	v_pk_fma_f32 v[232:233], v[232:233], v[212:213], v[212:213]
	v_pk_fma_f32 v[234:235], v[234:235], v[214:215], v[214:215]
	v_pk_fma_f32 v[236:237], v[236:237], v[220:221], v[220:221]
	v_pk_fma_f32 v[238:239], v[238:239], v[222:223], v[222:223]
	v_pk_mul_f32 v[224:225], v[224:225], v[160:161] op_sel_hi:[1,0]
	v_pk_mul_f32 v[226:227], v[226:227], v[160:161] op_sel_hi:[1,0]
	v_pk_mul_f32 v[228:229], v[228:229], v[160:161] op_sel_hi:[1,0]
	v_pk_mul_f32 v[230:231], v[230:231], v[160:161] op_sel_hi:[1,0]
	v_pk_mul_f32 v[232:233], v[232:233], v[160:161] op_sel_hi:[1,0]
	v_pk_mul_f32 v[234:235], v[234:235], v[160:161] op_sel_hi:[1,0]
	v_pk_mul_f32 v[236:237], v[236:237], v[160:161] op_sel_hi:[1,0]
	v_pk_mul_f32 v[238:239], v[238:239], v[160:161] op_sel_hi:[1,0]
	v_pk_add_f32 v[224:225], v[224:225], v[224:225]
	v_pk_add_f32 v[226:227], v[226:227], v[226:227]
	v_pk_add_f32 v[228:229], v[228:229], v[228:229]
	v_pk_add_f32 v[230:231], v[230:231], v[230:231]
	v_pk_add_f32 v[232:233], v[232:233], v[232:233]
	v_pk_add_f32 v[234:235], v[234:235], v[234:235]
	v_pk_add_f32 v[236:237], v[236:237], v[236:237]
	v_pk_add_f32 v[238:239], v[238:239], v[238:239]
	v_pk_mul_f32 v[224:225], v[224:225], v[162:163] op_sel_hi:[1,0]
	v_pk_mul_f32 v[226:227], v[226:227], v[162:163] op_sel_hi:[1,0]
	v_pk_mul_f32 v[228:229], v[228:229], v[162:163] op_sel_hi:[1,0]
	v_pk_mul_f32 v[230:231], v[230:231], v[162:163] op_sel_hi:[1,0]
	v_pk_mul_f32 v[232:233], v[232:233], v[162:163] op_sel_hi:[1,0]
	v_pk_mul_f32 v[234:235], v[234:235], v[162:163] op_sel_hi:[1,0]
	v_pk_mul_f32 v[236:237], v[236:237], v[162:163] op_sel_hi:[1,0]
	v_pk_mul_f32 v[238:239], v[238:239], v[162:163] op_sel_hi:[1,0]
	v_exp_f32_e32 v224, v224
	v_exp_f32_e32 v225, v225
	v_exp_f32_e32 v226, v226
	v_exp_f32_e32 v227, v227
	v_exp_f32_e32 v228, v228
	v_exp_f32_e32 v229, v229
	v_exp_f32_e32 v230, v230
	v_exp_f32_e32 v231, v231
	v_exp_f32_e32 v232, v232
	v_exp_f32_e32 v233, v233
	v_exp_f32_e32 v234, v234
	v_exp_f32_e32 v235, v235
	v_exp_f32_e32 v236, v236
	v_exp_f32_e32 v237, v237
	v_exp_f32_e32 v238, v238
	v_exp_f32_e32 v239, v239
	v_pk_mul_f32 v[204:205], v[204:205], 0.5 op_sel_hi:[1,0]
	v_pk_mul_f32 v[206:207], v[206:207], 0.5 op_sel_hi:[1,0]
	v_pk_mul_f32 v[208:209], v[208:209], 0.5 op_sel_hi:[1,0]
	v_pk_mul_f32 v[210:211], v[210:211], 0.5 op_sel_hi:[1,0]
	v_pk_mul_f32 v[212:213], v[212:213], 0.5 op_sel_hi:[1,0]
	v_pk_mul_f32 v[214:215], v[214:215], 0.5 op_sel_hi:[1,0]
	v_pk_mul_f32 v[220:221], v[220:221], 0.5 op_sel_hi:[1,0]
	v_pk_mul_f32 v[222:223], v[222:223], 0.5 op_sel_hi:[1,0]
	v_pk_add_f32 v[224:225], v[224:225], 1.0 op_sel_hi:[1,0]
	v_pk_add_f32 v[226:227], v[226:227], 1.0 op_sel_hi:[1,0]
	v_pk_add_f32 v[228:229], v[228:229], 1.0 op_sel_hi:[1,0]
	v_pk_add_f32 v[230:231], v[230:231], 1.0 op_sel_hi:[1,0]
	v_pk_add_f32 v[232:233], v[232:233], 1.0 op_sel_hi:[1,0]
	v_pk_add_f32 v[234:235], v[234:235], 1.0 op_sel_hi:[1,0]
	v_pk_add_f32 v[236:237], v[236:237], 1.0 op_sel_hi:[1,0]
	v_pk_add_f32 v[238:239], v[238:239], 1.0 op_sel_hi:[1,0]
	v_rcp_f32_e32 v224, v224
	v_rcp_f32_e32 v225, v225
	v_rcp_f32_e32 v226, v226
	v_rcp_f32_e32 v227, v227
	v_rcp_f32_e32 v228, v228
	v_rcp_f32_e32 v229, v229
	v_rcp_f32_e32 v230, v230
	v_rcp_f32_e32 v231, v231
	v_rcp_f32_e32 v232, v232
	v_rcp_f32_e32 v233, v233
	v_rcp_f32_e32 v234, v234
	v_rcp_f32_e32 v235, v235
	v_rcp_f32_e32 v236, v236
	v_rcp_f32_e32 v237, v237
	v_rcp_f32_e32 v238, v238
	v_rcp_f32_e32 v239, v239
	v_pk_fma_f32 v[224:225], v[224:225], -2.0, 1.0 op_sel_hi:[1,0,0]
	v_pk_fma_f32 v[226:227], v[226:227], -2.0, 1.0 op_sel_hi:[1,0,0]
	v_pk_fma_f32 v[228:229], v[228:229], -2.0, 1.0 op_sel_hi:[1,0,0]
	v_pk_fma_f32 v[230:231], v[230:231], -2.0, 1.0 op_sel_hi:[1,0,0]
	v_pk_fma_f32 v[232:233], v[232:233], -2.0, 1.0 op_sel_hi:[1,0,0]
	v_pk_fma_f32 v[234:235], v[234:235], -2.0, 1.0 op_sel_hi:[1,0,0]
	v_pk_fma_f32 v[236:237], v[236:237], -2.0, 1.0 op_sel_hi:[1,0,0]
	v_pk_fma_f32 v[238:239], v[238:239], -2.0, 1.0 op_sel_hi:[1,0,0]
	v_pk_add_f32 v[224:225], v[224:225], 1.0 op_sel_hi:[1,0]
	v_pk_add_f32 v[226:227], v[226:227], 1.0 op_sel_hi:[1,0]
	v_pk_add_f32 v[228:229], v[228:229], 1.0 op_sel_hi:[1,0]
	v_pk_add_f32 v[230:231], v[230:231], 1.0 op_sel_hi:[1,0]
	v_pk_add_f32 v[232:233], v[232:233], 1.0 op_sel_hi:[1,0]
	v_pk_add_f32 v[234:235], v[234:235], 1.0 op_sel_hi:[1,0]
	v_pk_add_f32 v[236:237], v[236:237], 1.0 op_sel_hi:[1,0]
	v_pk_add_f32 v[238:239], v[238:239], 1.0 op_sel_hi:[1,0]
	v_pk_mul_f32 v[204:205], v[204:205], v[224:225]
	v_pk_mul_f32 v[206:207], v[206:207], v[226:227]
	v_pk_mul_f32 v[208:209], v[208:209], v[228:229]
	v_pk_mul_f32 v[210:211], v[210:211], v[230:231]
	v_pk_mul_f32 v[212:213], v[212:213], v[232:233]
	v_pk_mul_f32 v[214:215], v[214:215], v[234:235]
	v_pk_mul_f32 v[220:221], v[220:221], v[236:237]
	v_pk_mul_f32 v[222:223], v[222:223], v[238:239]
	s_waitcnt lgkmcnt(0)
	v_pk_mul_f32 v[204:205], v[204:205], v[188:189]
	v_pk_mul_f32 v[206:207], v[206:207], v[190:191]
	v_pk_mul_f32 v[208:209], v[208:209], v[192:193]
	v_pk_mul_f32 v[210:211], v[210:211], v[194:195]
	v_pk_mul_f32 v[212:213], v[212:213], v[196:197]
	v_pk_mul_f32 v[214:215], v[214:215], v[198:199]
	v_pk_mul_f32 v[220:221], v[220:221], v[200:201]
	v_pk_mul_f32 v[222:223], v[222:223], v[202:203]
	v_cvt_pk_bf16_f32 v116, v204, v205
	v_cvt_pk_bf16_f32 v117, v206, v207
	v_cvt_pk_bf16_f32 v118, v208, v209
	v_cvt_pk_bf16_f32 v119, v210, v211
	v_cvt_pk_bf16_f32 v120, v212, v213
	v_cvt_pk_bf16_f32 v121, v214, v215
	v_cvt_pk_bf16_f32 v122, v220, v221
	v_cvt_pk_bf16_f32 v123, v222, v223
	global_store_dwordx4 v[34:35], v[116:119], off
	global_store_dwordx4 v[34:35], v[120:123], off offset:16
	s_cbranch_vccnz .LBB0_453
